# attn: replace per-lane 64-bit address arithmetic for K/V tile loads by scalar row bases + constant lane offsets; K batch-1 LDS reads hoisted above loads
# speedup vs baseline: 1.0062x; 1.0062x over previous
.LBB0_251:
	s_or_b64 exec, exec, s[8:9]
	s_and_b32 s0, s10, 0x780
	s_sub_i32 s17, s3, s0
	s_lshl_b32 s0, s12, 3
	s_and_b32 s15, s0, 0xfffff800
	s_bfe_u32 s14, s12, 0x10004
	s_ashr_i32 s16, s15, 31
	s_mul_i32 s8, s15, 0xa080
	s_mul_hi_i32 s0, s15, 0xa080
	s_add_u32 s9, s4, s8
	s_addc_u32 s18, s5, s0
	s_lshl_b32 s13, s19, 8
	s_lshl_b32 s0, s19, 9
	s_lshl_b32 s8, s14, 8
	s_add_u32 s20, s9, s0
	s_addc_u32 s21, s18, 0
	s_add_u32 s22, s20, s8
	v_lshlrev_b32_e32 v0, 4, v16
	s_addc_u32 s23, s21, 0
	s_add_u32 s24, s22, 0x7000
	s_addc_u32 s25, s23, 0
	v_and_b32_e32 v26, 0xf0, v0
	v_mov_b32_e32 v27, v65
	v_lshl_add_u64 v[0:1], s[22:23], 0, v[26:27]
	s_mov_b64 s[22:23], 0x7000
	v_lshl_add_u64 v[154:155], v[0:1], 0, s[22:23]
	v_ashrrev_i32_e32 v161, 4, v16
	v_add_u32_e32 v27, 0x200, v16
	v_mad_i64_i32 v[0:1], s[22:23], v161, s69, v[154:155]
	v_ashrrev_i32_e32 v162, 4, v27
	v_mad_i64_i32 v[2:3], s[22:23], v162, s69, v[154:155]
	global_load_dwordx4 v[18:21], v[0:1], off
	global_load_dwordx4 v[22:25], v[2:3], off
	v_lshlrev_b32_e32 v0, 2, v16
	v_and_b32_e32 v0, 0x1fc, v0
	v_mov_b32_e32 v1, v65
	v_lshl_add_u64 v[0:1], s[20:21], 0, v[0:1]
	s_add_u32 s26, s20, 0x8000
	s_addc_u32 s27, s21, 0
	s_mov_b64 s[20:21], 0x8000
	v_lshl_add_u64 v[156:157], v[0:1], 0, s[20:21]
	v_and_b32_e32 v163, -8, v161
	v_mad_i64_i32 v[0:1], s[20:21], v163, s69, v[156:157]
	v_add_co_u32_e32 v2, vcc, s89, v0
	v_and_b32_e32 v164, -8, v162
	v_and_b32_e32 v246, 15, v190
	v_mul_u32_u24_e32 v247, 0xa080, v161
	v_lshl_add_u32 v246, v246, 4, v247
	v_add_u32_e32 v247, 0x141000, v246
	v_and_b32_e32 v248, 0x7f, v190
	v_mul_u32_u24_e32 v249, 0xa080, v163
	v_lshl_add_u32 v248, v248, 2, v249
	v_add_u32_e32 v249, 0xa080, v248
	v_add_u32_e32 v250, 0x141000, v248
	v_add_u32_e32 v251, 0x14b080, v248
	s_nop 0
	v_addc_co_u32_e32 v3, vcc, 0, v1, vcc
	s_waitcnt vmcnt(5)
	v_add_co_u32_e32 v4, vcc, s93, v0
	s_lshl_b32 s18, s12, 7
	s_nop 0
	v_addc_co_u32_e32 v5, vcc, 0, v1, vcc
	v_add_co_u32_e32 v6, vcc, s91, v0
	s_and_b32 s18, s18, 0x780
	s_nop 0
	v_addc_co_u32_e32 v7, vcc, 0, v1, vcc
	s_waitcnt vmcnt(4)
	v_add_co_u32_e32 v8, vcc, s43, v0
	s_add_i32 s18, s18, s2
	s_nop 0
	v_addc_co_u32_e32 v9, vcc, 0, v1, vcc
	v_add_co_u32_e32 v10, vcc, s44, v0
	s_lshl_b32 s19, s19, 2
	s_nop 0
	v_addc_co_u32_e32 v11, vcc, 0, v1, vcc
	s_waitcnt vmcnt(3)
	v_add_co_u32_e32 v12, vcc, s45, v0
	v_readlane_b32 s52, v252, 25
	s_nop 0
	v_addc_co_u32_e32 v13, vcc, 0, v1, vcc
	v_add_co_u32_e32 v14, vcc, s46, v0
	v_and_b32_e32 v165, 15, v16
	s_nop 0
	v_addc_co_u32_e32 v15, vcc, 0, v1, vcc
	global_load_dword v17, v[0:1], off
	global_load_dword v28, v[2:3], off offset:128
	global_load_dword v29, v[4:5], off offset:256
	global_load_dword v30, v[6:7], off offset:384
	global_load_dword v31, v[8:9], off offset:512
	global_load_dword v32, v[10:11], off offset:640
	global_load_dword v33, v[12:13], off offset:768
	global_load_dword v34, v[14:15], off offset:896
	v_mad_i64_i32 v[0:1], s[20:21], v164, s69, v[156:157]
	v_add_co_u32_e32 v2, vcc, s89, v0
	v_readlane_b32 s60, v252, 33
	s_nop 0
	v_addc_co_u32_e32 v3, vcc, 0, v1, vcc
	v_add_co_u32_e32 v4, vcc, s93, v0
	v_readlane_b32 s61, v252, 34
	s_nop 0
	v_addc_co_u32_e32 v5, vcc, 0, v1, vcc
	v_add_co_u32_e32 v6, vcc, s91, v0
	s_mov_b32 s9, s1
	s_nop 0
	v_addc_co_u32_e32 v7, vcc, 0, v1, vcc
	v_add_co_u32_e32 v8, vcc, s43, v0
	v_bfe_u32 v43, v16, 4, 2
	s_nop 0
	v_addc_co_u32_e32 v9, vcc, 0, v1, vcc
	v_add_co_u32_e32 v10, vcc, s44, v0
	v_lshlrev_b32_e32 v64, 4, v43
	s_nop 0
	v_addc_co_u32_e32 v11, vcc, 0, v1, vcc
	v_add_co_u32_e32 v12, vcc, s45, v0
	v_add_u32_e32 v26, 0, v26
	s_nop 0
	v_addc_co_u32_e32 v13, vcc, 0, v1, vcc
	v_add_co_u32_e32 v14, vcc, s46, v0
	v_lshlrev_b32_e32 v158, 3, v43
	s_nop 0
	v_addc_co_u32_e32 v15, vcc, 0, v1, vcc
	global_load_dword v35, v[0:1], off
	global_load_dword v36, v[2:3], off offset:128
	global_load_dword v37, v[4:5], off offset:256
	global_load_dword v38, v[6:7], off offset:384
	global_load_dword v39, v[8:9], off offset:512
	global_load_dword v40, v[10:11], off offset:640
	global_load_dword v41, v[12:13], off offset:768
	global_load_dword v42, v[14:15], off offset:896
	v_mov_b32_e32 v0, s19
	s_add_i32 s19, s18, s15
	global_load_dword v44, v0, s[60:61] offset:480
	global_load_dword v45, v0, s[60:61] offset:992
	v_or_b32_e32 v2, s19, v165
	v_mov_b64_e32 v[0:1], s[4:5]
	v_mad_i64_i32 v[0:1], s[20:21], v2, s69, v[0:1]
	v_lshl_add_u64 v[0:1], v[0:1], 0, s[0:1]
	v_lshl_add_u64 v[0:1], v[0:1], 0, s[8:9]
	v_lshl_add_u64 v[0:1], v[0:1], 0, v[64:65]
	s_movk_i32 s0, 0x6000
	v_add_co_u32_e32 v8, vcc, s0, v0
	s_movk_i32 s0, 0x110
	s_mov_b64 s[8:9], 0x6000
	v_mul_lo_u32 v46, v161, s0
	v_lshl_add_u64 v[12:13], v[0:1], 0, s[8:9]
	v_addc_co_u32_e32 v9, vcc, 0, v1, vcc
	v_add_u32_e32 v166, v26, v46
	global_load_dwordx4 v[0:3], v[12:13], off offset:64
	global_load_dwordx4 v[4:7], v[12:13], off offset:128
	s_nop 0
	global_load_dwordx4 v[8:11], v[8:9], off
	s_nop 0
	global_load_dwordx4 v[12:15], v[12:13], off offset:192
	s_waitcnt vmcnt(23)
	ds_write_b128 v166, v[18:21]
	v_mul_lo_u32 v18, v162, s0
	v_add_u32_e32 v167, v26, v18
	v_and_b32_e32 v18, 0x7f, v16
	v_ashrrev_i32_e32 v16, 3, v16
	v_mad_u32_u24 v46, v18, s38, 0
	v_and_b32_e32 v168, -16, v16
	s_waitcnt vmcnt(22)
	ds_write_b128 v167, v[22:25]
	v_add_u32_e32 v169, v46, v168
	s_cmp_lg_u32 0, -1
	v_mov_b32_e32 v66, v65
	v_mov_b32_e32 v67, v65
	v_add_u32_e32 v179, 0x11800, v46
	v_add_u32_e32 v180, 0x16000, v46
	s_waitcnt vmcnt(20)
	v_perm_b32 v18, v28, v17, s48
	v_perm_b32 v22, v28, v17, s49
	s_waitcnt vmcnt(18)
	v_perm_b32 v19, v30, v29, s48
	v_perm_b32 v23, v30, v29, s49
	s_waitcnt vmcnt(16)
	v_perm_b32 v20, v32, v31, s48
	v_perm_b32 v24, v32, v31, s49
	s_waitcnt vmcnt(14)
	v_perm_b32 v21, v34, v33, s48
	v_perm_b32 v25, v34, v33, s49
	ds_write_b128 v169, v[18:21] offset:34816
	ds_write_b128 v169, v[22:25] offset:53248
	v_ashrrev_i32_e32 v24, 3, v27
	v_and_b32_e32 v170, -16, v24
	v_add_u32_e32 v24, 64, v163
	v_mad_i64_i32 v[24:25], s[8:9], v24, s69, v[156:157]
	v_add_co_u32_e32 v26, vcc, s89, v24
	v_add_u32_e32 v171, v46, v170
	s_nop 0
	v_addc_co_u32_e32 v27, vcc, 0, v25, vcc
	v_add_co_u32_e32 v28, vcc, s93, v24
	v_mov_b32_e32 v221, 0xf149f2ca
	s_nop 0
	v_addc_co_u32_e32 v29, vcc, 0, v25, vcc
	v_add_co_u32_e32 v30, vcc, s91, v24
	v_mov_b32_e32 v222, 0
	s_nop 0
	v_addc_co_u32_e32 v31, vcc, 0, v25, vcc
	v_add_co_u32_e32 v32, vcc, s43, v24
	v_readlane_b32 s53, v252, 26
	s_nop 0
	v_addc_co_u32_e32 v33, vcc, 0, v25, vcc
	v_add_co_u32_e32 v34, vcc, s44, v24
	v_readlane_b32 s54, v252, 27
	v_readlane_b32 s55, v252, 28
	s_waitcnt vmcnt(12)
	v_perm_b32 v16, v36, v35, s48
	v_perm_b32 v20, v36, v35, s49
	v_addc_co_u32_e32 v35, vcc, 0, v25, vcc
	s_waitcnt vmcnt(10)
	v_perm_b32 v17, v38, v37, s48
	s_waitcnt vmcnt(8)
	v_perm_b32 v18, v40, v39, s48
	s_waitcnt vmcnt(6)
	v_perm_b32 v19, v42, v41, s48
	v_add_co_u32_e32 v36, vcc, s45, v24
	v_perm_b32 v21, v38, v37, s49
	v_perm_b32 v22, v40, v39, s49
	v_perm_b32 v23, v42, v41, s49
	ds_write_b128 v171, v[16:19] offset:34816
	ds_write_b128 v171, v[20:23] offset:53248
	v_add_u32_e32 v16, 64, v161
	v_add_u32_e32 v18, 64, v162
	v_addc_co_u32_e32 v37, vcc, 0, v25, vcc
	s_waitcnt lgkmcnt(0)
	s_barrier
	v_mad_i64_i32 v[16:17], s[8:9], v16, s69, v[154:155]
	v_mad_i64_i32 v[20:21], s[8:9], v18, s69, v[154:155]
	v_add_co_u32_e32 v38, vcc, s46, v24
	global_load_dwordx4 v[16:19], v[16:17], off
	s_nop 0
	global_load_dwordx4 v[20:23], v[20:21], off
	v_addc_co_u32_e32 v39, vcc, 0, v25, vcc
	global_load_dword v172, v[24:25], off
	global_load_dword v175, v[26:27], off offset:128
	global_load_dword v176, v[28:29], off offset:256
	global_load_dword v181, v[30:31], off offset:384
	global_load_dword v194, v[32:33], off offset:512
	global_load_dword v195, v[34:35], off offset:640
	global_load_dword v196, v[36:37], off offset:768
	global_load_dword v197, v[38:39], off offset:896
	v_add_u32_e32 v24, 64, v164
	v_mad_i64_i32 v[24:25], s[8:9], v24, s69, v[156:157]
	v_add_co_u32_e32 v26, vcc, s89, v24
	v_readlane_b32 s8, v254, 60
	s_nop 0
	v_addc_co_u32_e32 v27, vcc, 0, v25, vcc
	v_add_co_u32_e32 v28, vcc, s93, v24
	s_waitcnt vmcnt(15)
	v_mul_f32_e32 v173, 0x413504f3, v44
	v_addc_co_u32_e32 v29, vcc, 0, v25, vcc
	v_add_co_u32_e32 v30, vcc, s91, v24
	s_waitcnt vmcnt(14)
	v_mul_f32_e32 v174, 0x413504f3, v45
	v_addc_co_u32_e32 v31, vcc, 0, v25, vcc
	v_add_co_u32_e32 v32, vcc, s43, v24
	v_readlane_b32 s56, v252, 29
	s_nop 0
	v_addc_co_u32_e32 v33, vcc, 0, v25, vcc
	v_add_co_u32_e32 v34, vcc, s44, v24
	v_readlane_b32 s57, v252, 30
	s_nop 0
	v_addc_co_u32_e32 v35, vcc, 0, v25, vcc
	v_add_co_u32_e32 v36, vcc, s45, v24
	v_readlane_b32 s58, v252, 31
	s_nop 0
	v_addc_co_u32_e32 v37, vcc, 0, v25, vcc
	v_add_co_u32_e32 v38, vcc, s46, v24
	v_readlane_b32 s59, v252, 32
	s_nop 0
	v_addc_co_u32_e32 v39, vcc, 0, v25, vcc
	global_load_dword v198, v[24:25], off
	global_load_dword v199, v[26:27], off offset:128
	global_load_dword v200, v[28:29], off offset:256
	global_load_dword v201, v[30:31], off offset:384
	global_load_dword v202, v[32:33], off offset:512
	global_load_dword v203, v[34:35], off offset:640
	global_load_dword v204, v[36:37], off offset:768
	global_load_dword v205, v[38:39], off offset:896
	v_mad_u32_u24 v27, v165, s0, v64
	s_cselect_b32 s0, 0, 0
	s_cmp_lg_u32 s8, -1
	v_mad_u32_u24 v29, v165, s38, v158
	s_cselect_b32 s8, s8, 0
	v_mov_b32_e32 v64, v65
	v_lshlrev_b32_e32 v30, 2, v43
	v_add_u32_e32 v177, s0, v27
	v_add_u32_e32 v178, s8, v29
	s_add_i32 s8, s0, 0x4400
	s_add_i32 s0, s0, 0x11800
	v_mov_b64_e32 v[36:37], v[64:65]
	v_mov_b64_e32 v[44:45], v[64:65]
	v_mov_b64_e32 v[52:53], v[64:65]
	v_mov_b64_e32 v[60:61], v[64:65]
	v_mov_b64_e32 v[70:71], v[66:67]
	v_mov_b64_e32 v[78:79], v[66:67]
	v_mov_b64_e32 v[86:87], v[66:67]
	v_mov_b64_e32 v[94:95], v[66:67]
	v_mov_b64_e32 v[32:33], v[64:65]
	v_mov_b64_e32 v[40:41], v[64:65]
	v_mov_b64_e32 v[48:49], v[64:65]
	v_mov_b64_e32 v[56:57], v[64:65]
	v_mov_b64_e32 v[74:75], v[66:67]
	v_mov_b64_e32 v[82:83], v[66:67]
	v_mov_b64_e32 v[90:91], v[66:67]
	v_mov_b64_e32 v[98:99], v[66:67]
	s_mov_b32 s29, 0x504000
	s_add_u32 s72, s24, s29
	s_addc_u32 s73, s25, 0
	s_add_u32 s74, s26, s29
	s_addc_u32 s75, s27, 0
	s_add_u32 s76, s74, 0x14100
	s_addc_u32 s77, s75, 0
	s_add_u32 s78, s76, 0x14100
	s_addc_u32 s79, s77, 0
	s_add_u32 s80, s78, 0x14100
	s_addc_u32 s81, s79, 0
	v_add_u32_e32 v191, s8, v27
	v_add_u32_e32 v192, s0, v29
	v_sub_u32_e32 v193, v30, v165
	s_mov_b32 s0, -2
	v_mov_b64_e32 v[38:39], v[66:67]
	v_mov_b64_e32 v[46:47], v[66:67]
	v_mov_b64_e32 v[54:55], v[66:67]
	v_mov_b64_e32 v[62:63], v[66:67]
	v_mov_b64_e32 v[68:69], v[64:65]
	v_mov_b64_e32 v[76:77], v[64:65]
	v_mov_b64_e32 v[84:85], v[64:65]
	v_mov_b64_e32 v[92:93], v[64:65]
	v_mov_b64_e32 v[34:35], v[66:67]
	v_mov_b64_e32 v[42:43], v[66:67]
	v_mov_b64_e32 v[50:51], v[66:67]
	v_mov_b64_e32 v[58:59], v[66:67]
	v_mov_b64_e32 v[72:73], v[64:65]
	v_mov_b64_e32 v[80:81], v[64:65]
	v_mov_b64_e32 v[88:89], v[64:65]
	v_mov_b64_e32 v[96:97], v[64:65]
	v_readlane_b32 s62, v252, 35
	v_readlane_b32 s63, v252, 36
	v_readlane_b32 s64, v252, 37
	v_readlane_b32 s65, v252, 38
	v_readlane_b32 s66, v252, 39
	v_readlane_b32 s67, v252, 40
.LBB0_252:
	ds_read_b128 v[100:103], v177 offset:0
	ds_read_b128 v[104:107], v177 offset:64
	ds_read_b128 v[108:111], v177 offset:0x80
	ds_read_b128 v[112:115], v177 offset:0xc0
	ds_read_b128 v[116:119], v177 offset:0x1100
	ds_read_b128 v[120:123], v177 offset:0x1140
	ds_read_b128 v[124:127], v177 offset:0x1180
	ds_read_b128 v[128:131], v177 offset:0x11c0
	global_load_dword v64, v248, s[74:75]
	global_load_dword v206, v249, s[74:75]
	global_load_dword v207, v248, s[76:77]
	global_load_dword v208, v249, s[76:77]
	global_load_dword v209, v248, s[78:79]
	global_load_dword v210, v249, s[78:79]
	global_load_dword v211, v248, s[80:81]
	global_load_dword v212, v249, s[80:81]
	global_load_dword v213, v250, s[74:75]
	global_load_dword v214, v251, s[74:75]
	global_load_dword v215, v250, s[76:77]
	global_load_dword v216, v251, s[76:77]
	global_load_dword v217, v250, s[78:79]
	global_load_dword v218, v251, s[78:79]
	global_load_dword v219, v250, s[80:81]
	global_load_dword v220, v251, s[80:81]
	global_load_dwordx4 v[24:27], v246, s[72:73]
	global_load_dwordx4 v[28:31], v247, s[72:73]
	s_waitcnt lgkmcnt(0)
	s_waitcnt vmcnt(37)
	v_mfma_f32_16x16x32_bf16 v[100:103], v[100:103], v[8:11], 0
	v_mfma_f32_16x16x32_bf16 v[116:119], v[116:119], v[8:11], 0
	v_mfma_f32_16x16x32_bf16 v[100:103], v[104:107], v[0:3], v[100:103]
	v_mfma_f32_16x16x32_bf16 v[104:107], v[120:123], v[0:3], v[116:119]
	v_mfma_f32_16x16x32_bf16 v[100:103], v[108:111], v[4:7], v[100:103]
	v_mfma_f32_16x16x32_bf16 v[108:111], v[124:127], v[4:7], v[104:107]
	s_waitcnt vmcnt(36)
	v_mfma_f32_16x16x32_bf16 v[104:107], v[112:115], v[12:15], v[100:103]
	v_mfma_f32_16x16x32_bf16 v[100:103], v[128:131], v[12:15], v[108:111]
	ds_read_b128 v[108:111], v177 offset:0x2200
	ds_read_b128 v[112:115], v177 offset:0x2240
	ds_read_b128 v[116:119], v177 offset:0x2280
	ds_read_b128 v[120:123], v177 offset:0x22c0
	ds_read_b128 v[124:127], v177 offset:0x3300
	ds_read_b128 v[128:131], v177 offset:0x3340
	ds_read_b128 v[132:135], v177 offset:0x3380
	ds_read_b128 v[136:139], v177 offset:0x33c0
	s_waitcnt lgkmcnt(0)
	s_nop 4
	v_mfma_f32_16x16x32_bf16 v[108:111], v[108:111], v[8:11], 0
	s_add_i32 s8, s17, 0xffffff56
	s_cmp_lt_u32 s8, 0xfffffefd
	v_mfma_f32_16x16x32_bf16 v[108:111], v[112:115], v[0:3], v[108:111]
	v_mfma_f32_16x16x32_bf16 v[124:127], v[124:127], v[8:11], 0
	v_mfma_f32_16x16x32_bf16 v[108:111], v[116:119], v[4:7], v[108:111]
	ds_read_b64 v[116:117], v178 offset:0
	ds_read_b64 v[118:119], v178 offset:32
	v_mfma_f32_16x16x32_bf16 v[112:115], v[128:131], v[0:3], v[124:127]
	v_mfma_f32_16x16x32_bf16 v[128:131], v[120:123], v[12:15], v[108:111]
	ds_read_b64 v[108:109], v178 offset:64
	ds_read_b64 v[110:111], v178 offset:0x60
	ds_read_b64 v[120:121], v178 offset:0x900
	v_mfma_f32_16x16x32_bf16 v[112:115], v[132:135], v[4:7], v[112:115]
	ds_read_b64 v[122:123], v178 offset:0x920
	ds_read_b64 v[124:125], v178 offset:0x940
	ds_read_b64 v[126:127], v178 offset:0x960
	v_mfma_f32_16x16x32_bf16 v[112:115], v[136:139], v[12:15], v[112:115]
	ds_read_b64 v[136:137], v178 offset:0x1200
	ds_read_b64 v[138:139], v178 offset:0x1220
	ds_read_b64 v[132:133], v178 offset:0x1240
	ds_read_b64 v[134:135], v178 offset:0x1260
	ds_read_b64 v[140:141], v178 offset:0x1b00
	ds_read_b64 v[142:143], v178 offset:0x1b20
	ds_read_b64 v[144:145], v178 offset:0x1b40
	ds_read_b64 v[146:147], v178 offset:0x1b60
	s_cbranch_scc1 .LBB0_254
	v_add3_u32 v152, v193, s17, 64
	v_max_i32_e32 v67, -1, v152
	v_add_u32_e32 v67, 1, v67
	v_med3_i32 v66, v152, 0, v188
	s_add_i32 s8, 0, 0x1a800
	v_min_u32_e32 v67, 0x100, v67
	v_lshl_add_u32 v66, v66, 2, s8
	v_lshl_add_u32 v67, v67, 2, s8
	ds_read_b32 v66, v66
	ds_read_b32 v67, v67
	v_max_i32_e32 v153, -2, v152
	v_add_u32_e32 v153, 2, v153
	v_min_u32_e32 v153, 0x100, v153
	v_lshl_add_u32 v153, v153, 2, s8
	ds_read_b32 v224, v153
	v_max_i32_e32 v153, -3, v152
	s_waitcnt lgkmcnt(1)
	v_pk_add_f32 v[104:105], v[104:105], v[66:67]
	v_max_i32_e32 v66, -16, v152
	v_max_i32_e32 v67, 0xffffffef, v152
	v_add_u32_e32 v153, 3, v153
	v_add_u32_e32 v66, 16, v66
	v_add_u32_e32 v67, 17, v67
	v_min_u32_e32 v153, 0x100, v153
	v_min_u32_e32 v66, 0x100, v66
	v_min_u32_e32 v67, 0x100, v67
	v_lshl_add_u32 v153, v153, 2, s8
	v_lshl_add_u32 v66, v66, 2, s8
	v_lshl_add_u32 v67, v67, 2, s8
	ds_read_b32 v225, v153
	ds_read_b32 v66, v66
	ds_read_b32 v67, v67
	v_max_i32_e32 v153, 0xffffffee, v152
	v_add_u32_e32 v153, 18, v153
	v_min_u32_e32 v153, 0x100, v153
	v_lshl_add_u32 v153, v153, 2, s8
	s_waitcnt lgkmcnt(0)
	v_pk_add_f32 v[100:101], v[100:101], v[66:67]
	v_max_i32_e32 v66, 0xffffffe0, v152
	v_max_i32_e32 v67, 0xffffffdf, v152
	v_add_u32_e32 v66, 32, v66
	v_add_u32_e32 v67, 33, v67
	v_min_u32_e32 v66, 0x100, v66
	v_min_u32_e32 v67, 0x100, v67
	v_lshl_add_u32 v66, v66, 2, s8
	v_lshl_add_u32 v67, v67, 2, s8
	v_pk_add_f32 v[106:107], v[106:107], v[224:225]
	ds_read_b32 v224, v153
	ds_read_b32 v66, v66
	ds_read_b32 v67, v67
	v_max_i32_e32 v153, 0xffffffed, v152
	v_add_u32_e32 v153, 19, v153
	v_min_u32_e32 v153, 0x100, v153
	v_lshl_add_u32 v153, v153, 2, s8
	ds_read_b32 v225, v153
	v_max_i32_e32 v153, 0xffffffde, v152
	v_add_u32_e32 v153, 34, v153
	v_min_u32_e32 v153, 0x100, v153
	v_lshl_add_u32 v153, v153, 2, s8
	s_waitcnt lgkmcnt(0)
	v_pk_add_f32 v[102:103], v[102:103], v[224:225]
	ds_read_b32 v224, v153
	v_max_i32_e32 v153, 0xffffffdd, v152
	v_add_u32_e32 v153, 35, v153
	v_min_u32_e32 v153, 0x100, v153
	v_lshl_add_u32 v153, v153, 2, s8
	ds_read_b32 v225, v153
	v_pk_add_f32 v[128:129], v[128:129], v[66:67]
	v_max_i32_e32 v66, 0xffffffd0, v152
	v_max_i32_e32 v67, 0xffffffcf, v152
	v_max_i32_e32 v153, 0xffffffce, v152
	v_max_i32_e32 v152, 0xffffffcd, v152
	v_add_u32_e32 v66, 48, v66
	v_add_u32_e32 v67, 49, v67
	v_add_u32_e32 v153, 50, v153
	v_add_u32_e32 v152, 51, v152
	v_min_u32_e32 v66, 0x100, v66
	v_min_u32_e32 v67, 0x100, v67
	v_min_u32_e32 v153, 0x100, v153
	v_min_u32_e32 v152, 0x100, v152
	v_lshl_add_u32 v66, v66, 2, s8
	v_lshl_add_u32 v67, v67, 2, s8
	v_lshl_add_u32 v153, v153, 2, s8
	v_lshl_add_u32 v152, v152, 2, s8
	s_waitcnt lgkmcnt(0)
	v_pk_add_f32 v[130:131], v[130:131], v[224:225]
	ds_read_b32 v66, v66
	ds_read_b32 v67, v67
	ds_read_b32 v224, v153
	ds_read_b32 v225, v152
	s_waitcnt lgkmcnt(2)
	v_pk_add_f32 v[112:113], v[112:113], v[66:67]
	s_waitcnt lgkmcnt(0)
	v_pk_add_f32 v[114:115], v[114:115], v[224:225]

.LBB0_256:
	v_sub_f32_e32 v66, v66, v221
	v_mul_f32_e32 v66, 0x3e0293ee, v66
	v_fmamk_f32 v67, v104, 0x3e0293ee, v66
	v_exp_f32_e32 v223, v67
	v_fmamk_f32 v67, v105, 0x3e0293ee, v66
	v_exp_f32_e32 v224, v67
	v_fmamk_f32 v67, v106, 0x3e0293ee, v66
	v_exp_f32_e32 v225, v67
	v_fmamk_f32 v67, v107, 0x3e0293ee, v66
	v_exp_f32_e32 v226, v67
	v_fmamk_f32 v67, v100, 0x3e0293ee, v66
	v_exp_f32_e32 v227, v67
	v_fmamk_f32 v67, v101, 0x3e0293ee, v66
	v_exp_f32_e32 v228, v67
	v_fmamk_f32 v67, v102, 0x3e0293ee, v66
	v_exp_f32_e32 v229, v67
	v_fmamk_f32 v67, v103, 0x3e0293ee, v66
	v_exp_f32_e32 v230, v67
	v_fmamk_f32 v67, v128, 0x3e0293ee, v66
	v_exp_f32_e32 v231, v67
	v_fmamk_f32 v67, v129, 0x3e0293ee, v66
	v_exp_f32_e32 v232, v67
	v_fmamk_f32 v67, v130, 0x3e0293ee, v66
	v_exp_f32_e32 v233, v67
	v_fmamk_f32 v67, v131, 0x3e0293ee, v66
	v_exp_f32_e32 v234, v67
	v_fmamk_f32 v67, v112, 0x3e0293ee, v66
	v_exp_f32_e32 v235, v67
	v_fmamk_f32 v67, v113, 0x3e0293ee, v66
	v_exp_f32_e32 v236, v67
	v_fmamk_f32 v67, v114, 0x3e0293ee, v66
	v_fmac_f32_e32 v66, 0x3e0293ee, v115
	v_exp_f32_e32 v237, v67
	v_exp_f32_e32 v238, v66
	s_waitcnt lgkmcnt(0)
	s_add_i32 s8, s0, 2
	v_cvt_pk_bf16_f32 v104, v223, v224
	v_cvt_pk_bf16_f32 v105, v225, v226
	v_cvt_pk_bf16_f32 v106, v227, v228
	v_cvt_pk_bf16_f32 v107, v229, v230
	v_cvt_pk_bf16_f32 v100, v231, v232
	v_cvt_pk_bf16_f32 v101, v233, v234
	v_cvt_pk_bf16_f32 v102, v235, v236
	v_cvt_pk_bf16_f32 v103, v237, v238
	v_mfma_f32_16x16x32_bf16 v[96:99], v[116:119], v[104:107], v[96:99]
	s_nop 0
	v_mfma_f32_16x16x32_bf16 v[96:99], v[108:111], v[100:103], v[96:99]
	ds_read_b64 v[108:109], v178 offset:0x2400
	ds_read_b64 v[110:111], v178 offset:0x2420
	ds_read_b64 v[112:113], v178 offset:0x2440
	ds_read_b64 v[114:115], v178 offset:0x2460
	v_mfma_f32_16x16x32_bf16 v[88:91], v[120:123], v[104:107], v[88:91]
	ds_read_b64 v[116:117], v178 offset:0x2d00
	ds_read_b64 v[118:119], v178 offset:0x2d20
	ds_read_b64 v[120:121], v178 offset:0x2d40
	ds_read_b64 v[122:123], v178 offset:0x2d60
	v_mfma_f32_16x16x32_bf16 v[80:83], v[136:139], v[104:107], v[80:83]
	v_mfma_f32_16x16x32_bf16 v[88:91], v[124:127], v[100:103], v[88:91]
	ds_read_b64 v[124:125], v178 offset:0x3600
	ds_read_b64 v[126:127], v178 offset:0x3620
	ds_read_b64 v[128:129], v178 offset:0x3640
	v_mfma_f32_16x16x32_bf16 v[72:75], v[140:143], v[104:107], v[72:75]
	ds_read_b64 v[130:131], v178 offset:0x3660
	v_mfma_f32_16x16x32_bf16 v[80:83], v[132:135], v[100:103], v[80:83]
	ds_read_b64 v[132:133], v178 offset:0x3f00
	ds_read_b64 v[134:135], v178 offset:0x3f20
	ds_read_b64 v[136:137], v178 offset:0x3f40
	v_mfma_f32_16x16x32_bf16 v[72:75], v[144:147], v[100:103], v[72:75]
	ds_read_b64 v[138:139], v178 offset:0x3f60
	s_waitcnt lgkmcnt(0)
	v_mfma_f32_16x16x32_bf16 v[56:59], v[108:111], v[104:107], v[56:59]
	ds_read_b64 v[108:109], v178 offset:0x4800
	ds_read_b64 v[110:111], v178 offset:0x4820
	v_mfma_f32_16x16x32_bf16 v[48:51], v[116:119], v[104:107], v[48:51]
	v_mfma_f32_16x16x32_bf16 v[56:59], v[112:115], v[100:103], v[56:59]
	ds_read_b64 v[112:113], v178 offset:0x4840
	ds_read_b64 v[114:115], v178 offset:0x4860
	ds_read_b64 v[116:117], v178 offset:0x5100
	ds_read_b64 v[118:119], v178 offset:0x5120
	v_mfma_f32_16x16x32_bf16 v[40:43], v[124:127], v[104:107], v[40:43]
	v_mfma_f32_16x16x32_bf16 v[48:51], v[120:123], v[100:103], v[48:51]
	ds_read_b64 v[120:121], v178 offset:0x5140
	ds_read_b64 v[122:123], v178 offset:0x5160
	ds_read_b64 v[124:125], v178 offset:0x5a00
	ds_read_b64 v[126:127], v178 offset:0x5a20
	v_mfma_f32_16x16x32_bf16 v[32:35], v[132:135], v[104:107], v[32:35]
	v_mfma_f32_16x16x32_bf16 v[40:43], v[128:131], v[100:103], v[40:43]
	ds_read_b64 v[128:129], v178 offset:0x5a40
	ds_read_b64 v[130:131], v178 offset:0x5a60
	ds_read_b64 v[132:133], v178 offset:0x6300
	ds_read_b64 v[134:135], v178 offset:0x6320
	v_mfma_f32_16x16x32_bf16 v[32:35], v[136:139], v[100:103], v[32:35]
	ds_read_b64 v[136:137], v178 offset:0x6340
	ds_read_b64 v[138:139], v178 offset:0x6360
	s_waitcnt lgkmcnt(0)
	v_mfma_f32_16x16x32_bf16 v[92:95], v[108:111], v[104:107], v[92:95]
	ds_read_b64 v[108:109], v178 offset:0x6c00
	ds_read_b64 v[110:111], v178 offset:0x6c20
	v_mfma_f32_16x16x32_bf16 v[84:87], v[116:119], v[104:107], v[84:87]
	v_mfma_f32_16x16x32_bf16 v[92:95], v[112:115], v[100:103], v[92:95]
	ds_read_b64 v[112:113], v178 offset:0x6c40
	ds_read_b64 v[114:115], v178 offset:0x6c60
	ds_read_b64 v[116:117], v178 offset:0x7500
	ds_read_b64 v[118:119], v178 offset:0x7520
	v_mfma_f32_16x16x32_bf16 v[76:79], v[124:127], v[104:107], v[76:79]
	v_mfma_f32_16x16x32_bf16 v[84:87], v[120:123], v[100:103], v[84:87]
	ds_read_b64 v[120:121], v178 offset:0x7540
	ds_read_b64 v[122:123], v178 offset:0x7560
	ds_read_b64 v[124:125], v178 offset:0x7e00
	ds_read_b64 v[126:127], v178 offset:0x7e20
	v_mfma_f32_16x16x32_bf16 v[66:69], v[132:135], v[104:107], v[68:71]
	v_mfma_f32_16x16x32_bf16 v[76:79], v[128:131], v[100:103], v[76:79]
	ds_read_b64 v[128:129], v178 offset:0x7e40
	ds_read_b64 v[130:131], v178 offset:0x7e60
	ds_read_b64 v[132:133], v178 offset:0x8700
	ds_read_b64 v[134:135], v178 offset:0x8720
	v_mfma_f32_16x16x32_bf16 v[66:69], v[136:139], v[100:103], v[66:69]
	ds_read_b64 v[136:137], v178 offset:0x8740
	ds_read_b64 v[138:139], v178 offset:0x8760
	s_waitcnt lgkmcnt(0)
	v_mfma_f32_16x16x32_bf16 v[60:63], v[108:111], v[104:107], v[60:63]
	v_mfma_f32_16x16x32_bf16 v[52:55], v[116:119], v[104:107], v[52:55]
	v_mfma_f32_16x16x32_bf16 v[44:47], v[124:127], v[104:107], v[44:47]
	v_mfma_f32_16x16x32_bf16 v[36:39], v[132:135], v[104:107], v[36:39]
	v_mfma_f32_16x16x32_bf16 v[60:63], v[112:115], v[100:103], v[60:63]
	v_mfma_f32_16x16x32_bf16 v[52:55], v[120:123], v[100:103], v[52:55]
	v_mfma_f32_16x16x32_bf16 v[44:47], v[128:131], v[100:103], v[44:47]
	v_mfma_f32_16x16x32_bf16 v[36:39], v[136:139], v[100:103], v[36:39]
	s_waitcnt vmcnt(29)
	ds_write_b128 v166, v[16:19] offset:17408
	s_waitcnt vmcnt(24)
	ds_write_b128 v167, v[20:23] offset:17408
	s_waitcnt vmcnt(32)
	v_perm_b32 v16, v175, v172, s48
	s_waitcnt vmcnt(30)
	v_perm_b32 v17, v181, v176, s48
	s_waitcnt vmcnt(28)
	v_perm_b32 v18, v195, v194, s48
	s_waitcnt vmcnt(26)
	v_perm_b32 v19, v197, v196, s48
	v_add_u32_e32 v70, v179, v168
	s_min_u32 s9, s8, 28
	v_perm_b32 v20, v175, v172, s49
	v_perm_b32 v21, v181, v176, s49
	v_perm_b32 v22, v195, v194, s49
	v_perm_b32 v23, v197, v196, s49
	ds_write_b128 v70, v[16:19]
	v_add_u32_e32 v16, v180, v168
	s_lshl_b32 s9, s9, 6
	ds_write_b128 v16, v[20:23]
	s_waitcnt vmcnt(24)
	v_perm_b32 v16, v199, v198, s48
	s_waitcnt vmcnt(22)
	v_perm_b32 v17, v201, v200, s48
	s_waitcnt vmcnt(20)
	v_perm_b32 v18, v203, v202, s48
	s_waitcnt vmcnt(18)
	v_perm_b32 v19, v205, v204, s48
	v_add_u32_e32 v70, v179, v170
	s_addk_i32 s9, 0xc0
	s_mul_i32 s29, s9, 0xa080
	s_add_u32 s72, s24, s29
	s_addc_u32 s73, s25, 0
	s_add_u32 s74, s26, s29
	s_addc_u32 s75, s27, 0
	s_add_u32 s76, s74, 0x14100
	s_addc_u32 s77, s75, 0
	s_add_u32 s78, s76, 0x14100
	s_addc_u32 s79, s77, 0
	s_add_u32 s80, s78, 0x14100
	s_addc_u32 s81, s79, 0
	ds_write_b128 v70, v[16:19]
	v_perm_b32 v20, v199, v198, s49
	v_perm_b32 v21, v201, v200, s49
	v_perm_b32 v22, v203, v202, s49
	v_perm_b32 v23, v205, v204, s49
	v_add_u32_e32 v16, v180, v170
	ds_write_b128 v16, v[20:23]
	s_waitcnt lgkmcnt(0)
	s_barrier
	ds_read_b128 v[100:103], v191 offset:0
	ds_read_b128 v[104:107], v191 offset:64
	ds_read_b128 v[108:111], v191 offset:0x80
	ds_read_b128 v[112:115], v191 offset:0xc0
	ds_read_b128 v[116:119], v191 offset:0x1100
	ds_read_b128 v[120:123], v191 offset:0x1140
	ds_read_b128 v[124:127], v191 offset:0x1180
	ds_read_b128 v[128:131], v191 offset:0x11c0
	global_load_dword v172, v248, s[74:75]
	global_load_dword v175, v249, s[74:75]
	global_load_dword v176, v248, s[76:77]
	global_load_dword v181, v249, s[76:77]
	global_load_dword v194, v248, s[78:79]
	global_load_dword v195, v249, s[78:79]
	global_load_dwordx4 v[16:19], v246, s[72:73]
	global_load_dword v196, v248, s[80:81]
	global_load_dword v197, v249, s[80:81]
	global_load_dword v198, v250, s[74:75]
	global_load_dword v199, v251, s[74:75]
	global_load_dwordx4 v[20:23], v247, s[72:73]
	global_load_dword v200, v250, s[76:77]
	global_load_dword v201, v251, s[76:77]
	global_load_dword v202, v250, s[78:79]
	global_load_dword v203, v251, s[78:79]
	global_load_dword v204, v250, s[80:81]
	global_load_dword v205, v251, s[80:81]
	s_waitcnt lgkmcnt(0)
	s_nop 0
	v_mfma_f32_16x16x32_bf16 v[100:103], v[100:103], v[8:11], 0
	v_mfma_f32_16x16x32_bf16 v[116:119], v[116:119], v[8:11], 0
	v_mfma_f32_16x16x32_bf16 v[100:103], v[104:107], v[0:3], v[100:103]
	v_mfma_f32_16x16x32_bf16 v[104:107], v[120:123], v[0:3], v[116:119]
	v_mfma_f32_16x16x32_bf16 v[100:103], v[108:111], v[4:7], v[100:103]
	v_mfma_f32_16x16x32_bf16 v[104:107], v[124:127], v[4:7], v[104:107]
	v_mfma_f32_16x16x32_bf16 v[112:115], v[112:115], v[12:15], v[100:103]
	v_mfma_f32_16x16x32_bf16 v[100:103], v[128:131], v[12:15], v[104:107]
	ds_read_b128 v[104:107], v191 offset:0x2200
	ds_read_b128 v[108:111], v191 offset:0x2240
	ds_read_b128 v[116:119], v191 offset:0x2280
	ds_read_b128 v[120:123], v191 offset:0x22c0
	ds_read_b128 v[124:127], v191 offset:0x3300
	ds_read_b128 v[128:131], v191 offset:0x3340
	ds_read_b128 v[132:135], v191 offset:0x3380
	ds_read_b128 v[136:139], v191 offset:0x33c0
	s_waitcnt lgkmcnt(0)
	s_nop 5
	v_mfma_f32_16x16x32_bf16 v[104:107], v[104:107], v[8:11], 0
	s_add_i32 s9, s17, 0xffffff96
	s_cmp_lt_u32 s9, 0xfffffefd
	v_mfma_f32_16x16x32_bf16 v[104:107], v[108:111], v[0:3], v[104:107]
	v_mfma_f32_16x16x32_bf16 v[124:127], v[124:127], v[8:11], 0
	v_mfma_f32_16x16x32_bf16 v[104:107], v[116:119], v[4:7], v[104:107]
	ds_read_b64 v[116:117], v192 offset:0
	ds_read_b64 v[118:119], v192 offset:32
	v_mfma_f32_16x16x32_bf16 v[108:111], v[128:131], v[0:3], v[124:127]
	v_mfma_f32_16x16x32_bf16 v[128:131], v[120:123], v[12:15], v[104:107]
	ds_read_b64 v[104:105], v192 offset:64
	ds_read_b64 v[106:107], v192 offset:0x60
	ds_read_b64 v[120:121], v192 offset:0x900
	v_mfma_f32_16x16x32_bf16 v[108:111], v[132:135], v[4:7], v[108:111]
	ds_read_b64 v[122:123], v192 offset:0x920
	ds_read_b64 v[124:125], v192 offset:0x940
	ds_read_b64 v[126:127], v192 offset:0x960
	v_mfma_f32_16x16x32_bf16 v[108:111], v[136:139], v[12:15], v[108:111]
	ds_read_b64 v[136:137], v192 offset:0x1200
	ds_read_b64 v[138:139], v192 offset:0x1220
	ds_read_b64 v[132:133], v192 offset:0x1240
	ds_read_b64 v[134:135], v192 offset:0x1260
	ds_read_b64 v[140:141], v192 offset:0x1b00
	ds_read_b64 v[142:143], v192 offset:0x1b20
	ds_read_b64 v[144:145], v192 offset:0x1b40
	ds_read_b64 v[146:147], v192 offset:0x1b60
	s_cbranch_scc1 .LBB0_258
	v_add_u32_e32 v70, s17, v193
	v_add_u32_e32 v152, 0x80, v70
	v_max_i32_e32 v71, -1, v152
	v_add_u32_e32 v71, 1, v71
	v_med3_i32 v70, v152, 0, v188
	s_add_i32 s9, 0, 0x1a800
	v_min_u32_e32 v71, 0x100, v71
	v_lshl_add_u32 v70, v70, 2, s9
	v_lshl_add_u32 v71, v71, 2, s9
	ds_read_b32 v70, v70
	ds_read_b32 v71, v71
	v_max_i32_e32 v153, -2, v152
	v_add_u32_e32 v153, 2, v153
	v_min_u32_e32 v153, 0x100, v153
	v_lshl_add_u32 v153, v153, 2, s9
	ds_read_b32 v240, v153
	v_max_i32_e32 v153, -3, v152
	s_waitcnt lgkmcnt(1)
	v_pk_add_f32 v[112:113], v[112:113], v[70:71]
	v_max_i32_e32 v70, -16, v152
	v_max_i32_e32 v71, 0xffffffef, v152
	v_add_u32_e32 v153, 3, v153
	v_add_u32_e32 v70, 16, v70
	v_add_u32_e32 v71, 17, v71
	v_min_u32_e32 v153, 0x100, v153
	v_min_u32_e32 v70, 0x100, v70
	v_min_u32_e32 v71, 0x100, v71
	v_lshl_add_u32 v153, v153, 2, s9
	v_lshl_add_u32 v70, v70, 2, s9
	v_lshl_add_u32 v71, v71, 2, s9
	ds_read_b32 v241, v153
	ds_read_b32 v70, v70
	ds_read_b32 v71, v71
	v_max_i32_e32 v153, 0xffffffee, v152
	v_add_u32_e32 v153, 18, v153
	v_min_u32_e32 v153, 0x100, v153
	v_lshl_add_u32 v153, v153, 2, s9
	s_waitcnt lgkmcnt(0)
	v_pk_add_f32 v[100:101], v[100:101], v[70:71]
	v_max_i32_e32 v70, 0xffffffe0, v152
	v_max_i32_e32 v71, 0xffffffdf, v152
	v_add_u32_e32 v70, 32, v70
	v_add_u32_e32 v71, 33, v71
	v_min_u32_e32 v70, 0x100, v70
	v_min_u32_e32 v71, 0x100, v71
	v_lshl_add_u32 v70, v70, 2, s9
	v_lshl_add_u32 v71, v71, 2, s9
	v_pk_add_f32 v[114:115], v[114:115], v[240:241]
	ds_read_b32 v240, v153
	ds_read_b32 v70, v70
	ds_read_b32 v71, v71
	v_max_i32_e32 v153, 0xffffffed, v152
	v_add_u32_e32 v153, 19, v153
	v_min_u32_e32 v153, 0x100, v153
	v_lshl_add_u32 v153, v153, 2, s9
	ds_read_b32 v241, v153
	v_max_i32_e32 v153, 0xffffffde, v152
	v_add_u32_e32 v153, 34, v153
	v_min_u32_e32 v153, 0x100, v153
	v_lshl_add_u32 v153, v153, 2, s9
	s_waitcnt lgkmcnt(0)
	v_pk_add_f32 v[102:103], v[102:103], v[240:241]
	ds_read_b32 v240, v153
	v_max_i32_e32 v153, 0xffffffdd, v152
	v_add_u32_e32 v153, 35, v153
	v_min_u32_e32 v153, 0x100, v153
	v_lshl_add_u32 v153, v153, 2, s9
	ds_read_b32 v241, v153
	v_pk_add_f32 v[128:129], v[128:129], v[70:71]
	v_max_i32_e32 v70, 0xffffffd0, v152
	v_max_i32_e32 v71, 0xffffffcf, v152
	v_max_i32_e32 v153, 0xffffffce, v152
	v_max_i32_e32 v152, 0xffffffcd, v152
	v_add_u32_e32 v70, 48, v70
	v_add_u32_e32 v71, 49, v71
	v_add_u32_e32 v153, 50, v153
	v_add_u32_e32 v152, 51, v152
	v_min_u32_e32 v70, 0x100, v70
	v_min_u32_e32 v71, 0x100, v71
	v_min_u32_e32 v153, 0x100, v153
	v_min_u32_e32 v152, 0x100, v152
	v_lshl_add_u32 v70, v70, 2, s9
	v_lshl_add_u32 v71, v71, 2, s9
	v_lshl_add_u32 v153, v153, 2, s9
	v_lshl_add_u32 v152, v152, 2, s9
	s_waitcnt lgkmcnt(0)
	v_pk_add_f32 v[130:131], v[130:131], v[240:241]
	ds_read_b32 v70, v70
	ds_read_b32 v71, v71
	ds_read_b32 v240, v153
	ds_read_b32 v241, v152
	s_waitcnt lgkmcnt(2)
	v_pk_add_f32 v[108:109], v[108:109], v[70:71]
	s_waitcnt lgkmcnt(0)
	v_pk_add_f32 v[110:111], v[110:111], v[240:241]

.LBB0_260:
	v_sub_f32_e32 v70, v70, v221
	v_mul_f32_e32 v70, 0x3e0293ee, v70
	v_fmamk_f32 v71, v112, 0x3e0293ee, v70
	v_exp_f32_e32 v71, v71
	v_fmamk_f32 v112, v113, 0x3e0293ee, v70
	v_exp_f32_e32 v112, v112
	v_fmamk_f32 v113, v114, 0x3e0293ee, v70
	v_exp_f32_e32 v113, v113
	v_fmamk_f32 v114, v115, 0x3e0293ee, v70
	v_exp_f32_e32 v114, v114
	v_fmamk_f32 v100, v100, 0x3e0293ee, v70
	v_add_f32_e32 v115, 0, v71
	v_exp_f32_e32 v100, v100
	v_fmamk_f32 v101, v101, 0x3e0293ee, v70
	v_add_f32_e32 v115, v112, v115
	v_exp_f32_e32 v101, v101
	v_fmamk_f32 v102, v102, 0x3e0293ee, v70
	v_add_f32_e32 v115, v113, v115
	v_exp_f32_e32 v102, v102
	v_fmamk_f32 v103, v103, 0x3e0293ee, v70
	v_add_f32_e32 v115, v114, v115
	v_exp_f32_e32 v103, v103
	v_fmamk_f32 v128, v128, 0x3e0293ee, v70
	v_add_f32_e32 v115, v100, v115
	v_exp_f32_e32 v128, v128
	v_fmamk_f32 v129, v129, 0x3e0293ee, v70
	v_fmamk_f32 v108, v108, 0x3e0293ee, v70
	v_add_f32_e32 v115, v101, v115
	v_exp_f32_e32 v129, v129
	v_fmamk_f32 v130, v130, 0x3e0293ee, v70
	v_exp_f32_e32 v153, v108
	v_fmamk_f32 v108, v109, 0x3e0293ee, v70
	v_add_f32_e32 v115, v102, v115
	v_exp_f32_e32 v130, v130
	v_fmamk_f32 v131, v131, 0x3e0293ee, v70
	v_exp_f32_e32 v223, v108
	v_fmamk_f32 v108, v110, 0x3e0293ee, v70
	v_fmac_f32_e32 v70, 0x3e0293ee, v111
	v_add_f32_e32 v115, v103, v115
	v_exp_f32_e32 v131, v131
	v_exp_f32_e32 v224, v108
	v_exp_f32_e32 v225, v70
	v_add_f32_e32 v115, v128, v115
	s_waitcnt lgkmcnt(0)
	v_add_f32_e32 v115, v129, v115
	v_add_f32_e32 v115, v130, v115
	s_add_i32 s0, s0, 3
	v_add_f32_e32 v152, v131, v115
	v_cvt_pk_bf16_f32 v108, v71, v112
	v_cvt_pk_bf16_f32 v109, v113, v114
	v_cvt_pk_bf16_f32 v110, v100, v101
	v_cvt_pk_bf16_f32 v111, v102, v103
	v_cvt_pk_bf16_f32 v100, v128, v129
	v_cvt_pk_bf16_f32 v101, v130, v131
	v_cvt_pk_bf16_f32 v102, v153, v223
	v_cvt_pk_bf16_f32 v103, v224, v225
	v_mfma_f32_16x16x32_bf16 v[96:99], v[116:119], v[108:111], v[96:99]
	s_nop 0
	v_mfma_f32_16x16x32_bf16 v[96:99], v[104:107], v[100:103], v[96:99]
	ds_read_b64 v[104:105], v192 offset:0x2400
	ds_read_b64 v[106:107], v192 offset:0x2420
	ds_read_b64 v[112:113], v192 offset:0x2440
	ds_read_b64 v[114:115], v192 offset:0x2460
	v_mfma_f32_16x16x32_bf16 v[88:91], v[120:123], v[108:111], v[88:91]
	ds_read_b64 v[116:117], v192 offset:0x2d00
	ds_read_b64 v[118:119], v192 offset:0x2d20
	ds_read_b64 v[120:121], v192 offset:0x2d40
	ds_read_b64 v[122:123], v192 offset:0x2d60
	v_mfma_f32_16x16x32_bf16 v[80:83], v[136:139], v[108:111], v[80:83]
	v_mfma_f32_16x16x32_bf16 v[88:91], v[124:127], v[100:103], v[88:91]
	ds_read_b64 v[124:125], v192 offset:0x3600
	ds_read_b64 v[126:127], v192 offset:0x3620
	ds_read_b64 v[128:129], v192 offset:0x3640
	v_mfma_f32_16x16x32_bf16 v[70:73], v[140:143], v[108:111], v[72:75]
	ds_read_b64 v[130:131], v192 offset:0x3660
	v_mfma_f32_16x16x32_bf16 v[80:83], v[132:135], v[100:103], v[80:83]
	ds_read_b64 v[132:133], v192 offset:0x3f00
	ds_read_b64 v[134:135], v192 offset:0x3f20
	ds_read_b64 v[136:137], v192 offset:0x3f40
	v_mfma_f32_16x16x32_bf16 v[72:75], v[144:147], v[100:103], v[70:73]
	ds_read_b64 v[138:139], v192 offset:0x3f60
	s_waitcnt lgkmcnt(0)
	v_mfma_f32_16x16x32_bf16 v[56:59], v[104:107], v[108:111], v[56:59]
	ds_read_b64 v[104:105], v192 offset:0x4800
	ds_read_b64 v[106:107], v192 offset:0x4820
	v_mfma_f32_16x16x32_bf16 v[48:51], v[116:119], v[108:111], v[48:51]
	v_mfma_f32_16x16x32_bf16 v[56:59], v[112:115], v[100:103], v[56:59]
	ds_read_b64 v[112:113], v192 offset:0x4840
	ds_read_b64 v[114:115], v192 offset:0x4860
	ds_read_b64 v[116:117], v192 offset:0x5100
	ds_read_b64 v[118:119], v192 offset:0x5120
	v_mfma_f32_16x16x32_bf16 v[40:43], v[124:127], v[108:111], v[40:43]
	v_mfma_f32_16x16x32_bf16 v[48:51], v[120:123], v[100:103], v[48:51]
	ds_read_b64 v[120:121], v192 offset:0x5140
	ds_read_b64 v[122:123], v192 offset:0x5160
	ds_read_b64 v[124:125], v192 offset:0x5a00
	ds_read_b64 v[126:127], v192 offset:0x5a20
	v_mfma_f32_16x16x32_bf16 v[32:35], v[132:135], v[108:111], v[32:35]
	v_mfma_f32_16x16x32_bf16 v[40:43], v[128:131], v[100:103], v[40:43]
	ds_read_b64 v[128:129], v192 offset:0x5a40
	ds_read_b64 v[130:131], v192 offset:0x5a60
	ds_read_b64 v[132:133], v192 offset:0x6300
	ds_read_b64 v[134:135], v192 offset:0x6320
	v_mfma_f32_16x16x32_bf16 v[32:35], v[136:139], v[100:103], v[32:35]
	ds_read_b64 v[136:137], v192 offset:0x6340
	ds_read_b64 v[138:139], v192 offset:0x6360
	s_waitcnt lgkmcnt(0)
	v_mfma_f32_16x16x32_bf16 v[92:95], v[104:107], v[108:111], v[92:95]
	ds_read_b64 v[104:105], v192 offset:0x6c00
	ds_read_b64 v[106:107], v192 offset:0x6c20
	v_mfma_f32_16x16x32_bf16 v[84:87], v[116:119], v[108:111], v[84:87]
	v_mfma_f32_16x16x32_bf16 v[92:95], v[112:115], v[100:103], v[92:95]
	ds_read_b64 v[112:113], v192 offset:0x6c40
	ds_read_b64 v[114:115], v192 offset:0x6c60
	ds_read_b64 v[116:117], v192 offset:0x7500
	ds_read_b64 v[118:119], v192 offset:0x7520
	v_mfma_f32_16x16x32_bf16 v[76:79], v[124:127], v[108:111], v[76:79]
	v_mfma_f32_16x16x32_bf16 v[84:87], v[120:123], v[100:103], v[84:87]
	ds_read_b64 v[120:121], v192 offset:0x7540
	ds_read_b64 v[122:123], v192 offset:0x7560
	ds_read_b64 v[124:125], v192 offset:0x7e00
	ds_read_b64 v[126:127], v192 offset:0x7e20
	v_mfma_f32_16x16x32_bf16 v[66:69], v[132:135], v[108:111], v[66:69]
	v_mfma_f32_16x16x32_bf16 v[76:79], v[128:131], v[100:103], v[76:79]
	ds_read_b64 v[128:129], v192 offset:0x7e40
	ds_read_b64 v[130:131], v192 offset:0x7e60
	ds_read_b64 v[132:133], v192 offset:0x8700
	ds_read_b64 v[134:135], v192 offset:0x8720
	v_mfma_f32_16x16x32_bf16 v[68:71], v[136:139], v[100:103], v[66:69]
	ds_read_b64 v[136:137], v192 offset:0x8740
	ds_read_b64 v[138:139], v192 offset:0x8760
	s_waitcnt lgkmcnt(0)
	v_mfma_f32_16x16x32_bf16 v[60:63], v[104:107], v[108:111], v[60:63]
	v_mfma_f32_16x16x32_bf16 v[52:55], v[116:119], v[108:111], v[52:55]
	v_mfma_f32_16x16x32_bf16 v[44:47], v[124:127], v[108:111], v[44:47]
	v_mfma_f32_16x16x32_bf16 v[36:39], v[132:135], v[108:111], v[36:39]
	v_mfma_f32_16x16x32_bf16 v[60:63], v[112:115], v[100:103], v[60:63]
	v_mfma_f32_16x16x32_bf16 v[52:55], v[120:123], v[100:103], v[52:55]
	v_mfma_f32_16x16x32_bf16 v[44:47], v[128:131], v[100:103], v[44:47]
	v_mfma_f32_16x16x32_bf16 v[36:39], v[136:139], v[100:103], v[36:39]
	s_waitcnt vmcnt(19)
	ds_write_b128 v166, v[24:27]
	s_waitcnt vmcnt(18)
	ds_write_b128 v167, v[28:31]
	v_add_f32_e32 v24, v153, v152
	v_add_f32_e32 v24, v223, v24
	v_add_f32_e32 v24, v224, v24
	v_add_f32_e32 v66, v225, v24
	v_perm_b32 v24, v206, v64, s48
	v_perm_b32 v25, v208, v207, s48
	v_perm_b32 v26, v210, v209, s48
	v_perm_b32 v27, v212, v211, s48
	v_perm_b32 v28, v206, v64, s49
	v_perm_b32 v29, v208, v207, s49
	v_perm_b32 v30, v210, v209, s49
	v_perm_b32 v31, v212, v211, s49
	ds_write_b128 v169, v[24:27] offset:34816
	ds_write_b128 v169, v[28:31] offset:53248
	v_perm_b32 v24, v214, v213, s48
	v_perm_b32 v25, v216, v215, s48
	v_perm_b32 v26, v218, v217, s48
	v_perm_b32 v27, v220, v219, s48
	v_perm_b32 v28, v214, v213, s49
	v_perm_b32 v29, v216, v215, s49
	v_perm_b32 v30, v218, v217, s49
	v_perm_b32 v31, v220, v219, s49
	ds_write_b128 v171, v[24:27] offset:34816
	ds_write_b128 v171, v[28:31] offset:53248
	s_min_u32 s0, s0, 28
	s_waitcnt lgkmcnt(0)
	s_barrier
	s_lshl_b32 s0, s0, 6
	s_addk_i32 s0, 0xc0
	s_mul_i32 s29, s0, 0xa080
	s_add_u32 s72, s24, s29
	s_addc_u32 s73, s25, 0
	s_add_u32 s74, s26, s29
	s_addc_u32 s75, s27, 0
	s_add_u32 s76, s74, 0x14100
	s_addc_u32 s77, s75, 0
	s_add_u32 s78, s76, 0x14100
	s_addc_u32 s79, s77, 0
	s_add_u32 s80, s78, 0x14100
	s_addc_u32 s81, s79, 0
	s_addk_i32 s17, 0x80
	s_cmp_lt_u32 s8, 30
	v_add_f32_e32 v222, v222, v66
	s_cbranch_scc0 .LBB0_248
	s_mov_b32 s0, s8
	s_branch .LBB0_252
